# GEMM phase prologues de-serialised: second K-tile's DMA stages issued before the first tile's wait+barrier (8 prologues)
# speedup vs baseline: 1.0017x; 1.0017x over previous
; #define PG8_STAGE(bufoff, gbase, voff) do { _Pragma("unroll") for (int _i = 0; _i < 2; ++_i) \
;         __builtin_amdgcn_global_load_lds((const unsigned*)((const char*)(gbase) + (voff)[_i]), (PG8_LAS unsigned*)(lds + (bufoff) + ldsw + _i * 8192), 16, 0, 0); } while (0)
; #define PG8_WAIT_V(n) asm volatile("s_waitcnt vmcnt(" #n ")" ::: "memory")
; #define PG8_BAR __builtin_amdgcn_s_barrier()
;     __device__ __forceinline__ void operator()(const f32x4 (&acc)[2][2][4][2], const Unit& u, int wr, int wc, int fr, int fq) const {
;     ...
;             const int i0 = (cw & 63) >> 1;
;             float invf[4];
; #pragma unroll
;             for (int t = 0; t < 4; ++t) invf[t] = __builtin_amdgcn_exp2f(-(float)(i0 + t) * (13.287712379549449f / 32.0f));
; template <class Epi, class Sched, bool ALIGN_EPI>
; __device__ __forceinline__ void gemm_phase(PG8_LAS unsigned char* lds, const Gemm g, const Sched& S, const Epi& E) {
;     ...
;     const char* cA = (const char*)g.A + (size_t)cur.pm * tstepA; const char* cB = (const char*)g.Bt + (size_t)cur.pn * tstepB;
;     PG8_STAGE(PG8_SB(0, 0), cB, voffB); PG8_STAGE(PG8_SB(0, 1), cB + hstepB, voffB); PG8_STAGE(PG8_SA(0, 0), cA, voffA); PG8_STAGE(PG8_SA(0, 1), cA + hstepA, voffA);
;     if (wr == 1) PG8_BAR;
;     PG8_WAIT_V(2); PG8_BAR;
;     PG8_STAGE(PG8_SB(1, 0), cB + kstep, voffB); PG8_STAGE(PG8_SA(1, 0), cA + kstepA, voffA); PG8_STAGE(PG8_SB(1, 1), cB + hstepB + kstep, voffB);
;     PG8_WAIT_V(6); PG8_BAR;
.LBB0_397:
	s_lshl_b32 s4, s4, 5
	s_and_b32 s15, s4, 0x60
	s_lshl_b32 s39, s1, 6
	s_lshl_b32 s14, s1, 13
	s_lshl_b32 s16, s15, 7
	s_add_u32 s40, s94, 0xd000000
	s_mov_b64 s[8:9], 0x80
	s_addc_u32 s41, s95, 0
	s_add_i32 m0, s34, 0x18000
	v_lshl_add_u64 v[8:9], v[8:9], 0, s[8:9]
	global_load_lds_dwordx4 v[8:9], off
	v_lshl_add_u64 v[6:7], v[6:7], 0, s[8:9]
	s_add_i32 m0, s34, 0x1a000
	s_add_i32 s42, s34, 0x8000
	s_add_i32 s43, s34, 0xa000
	global_load_lds_dwordx4 v[6:7], off
	v_lshl_add_u64 v[2:3], v[2:3], 0, s[8:9]
	s_mov_b32 m0, s42
	s_add_u32 s10, s26, 0x80080
	global_load_lds_dwordx4 v[2:3], off
	v_lshl_add_u64 v[2:3], v[4:5], 0, s[8:9]
	s_mov_b32 m0, s43
	s_addc_u32 s11, s27, 0
	global_load_lds_dwordx4 v[2:3], off
	s_add_i32 m0, s34, 0x1c000
	v_lshl_add_u64 v[2:3], s[10:11], 0, v[134:135]
	global_load_lds_dwordx4 v[2:3], off
	v_lshl_add_u64 v[2:3], s[10:11], 0, v[130:131]
	s_add_i32 m0, s34, 0x1e000
	v_and_b32_e32 v158, 15, v13
	global_load_lds_dwordx4 v[2:3], off
	v_lshrrev_b32_e32 v3, 1, v13
	v_and_b32_e32 v2, 24, v3
	v_lshlrev_b32_e32 v4, 1, v2
	v_lshlrev_b32_e32 v5, 2, v158
	v_lshl_or_b32 v4, v158, 6, v4
	v_and_b32_e32 v6, 32, v5
	v_or_b32_e32 v2, s15, v2
	v_bitop3_b32 v7, v4, s14, v6 bitop3:0xde
	v_bitop3_b32 v159, v4, s16, v6 bitop3:0xde
	v_and_b32_e32 v4, 8, v3
	v_lshrrev_b32_e32 v3, 1, v2
	v_and_b32_e32 v3, 28, v3
	v_cvt_f32_ubyte0_e32 v8, v3
	v_mul_f32_e32 v8, 0xbed49a78, v8
	v_exp_f32_e32 v161, v8
	v_or_b32_e32 v8, 1, v3
	v_cvt_f32_ubyte0_e32 v8, v8
	v_mul_f32_e32 v8, 0xbed49a78, v8
	v_exp_f32_e32 v162, v8
	v_or_b32_e32 v8, 2, v3
	v_or_b32_e32 v3, 3, v3
	s_cmpk_lt_u32 s5, 0x100
	v_cvt_f32_ubyte0_e32 v3, v3
	s_sext_i32_i8 s4, s0
	s_cselect_b64 s[10:11], -1, 0
	v_mul_f32_e32 v3, 0xbed49a78, v3
	s_lshl_b32 s0, s1, 8
	v_exp_f32_e32 v164, v3
	s_add_i32 s0, s0, 0
	v_lshlrev_b32_e32 v3, 15, v15
	s_add_i32 s0, s0, 0x20400
	v_and_b32_e32 v3, 0xffff0000, v3
	v_add_u32_e32 v165, s0, v5
	v_lshl_add_u32 v3, v14, 12, v3
	v_and_b32_e32 v5, 1, v15
	v_cvt_f32_ubyte0_e32 v8, v8
	v_lshl_or_b32 v3, v5, 6, v3
	v_mul_f32_e32 v8, 0xbed49a78, v8
	v_lshl_add_u32 v140, v16, 1, v3
	v_lshlrev_b32_e32 v3, 15, v10
	v_exp_f32_e32 v163, v8
	v_and_b32_e32 v3, 0xffff0000, v3
	s_waitcnt vmcnt(8)
	s_barrier
	s_waitcnt vmcnt(6)
	v_lshl_add_u32 v3, v11, 12, v3
	v_and_b32_e32 v5, 1, v10
	v_lshlrev_b32_e32 v6, 4, v158
	v_lshl_or_b32 v3, v5, 6, v3
	s_add_i32 s45, 0, 0x10000
	s_add_i32 s46, 0, 0x14000
	v_or_b32_e32 v160, 0xfffffb00, v2
	s_ashr_i32 s44, s33, 31
	v_mov_b32_e32 v141, v139
	v_lshl_add_u32 v142, v12, 1, v3
	v_mov_b32_e32 v143, v139
	v_mov_b64_e32 v[144:145], 0x240
	v_mov_b64_e32 v[146:147], 0x23f
	v_add_u32_e32 v166, s45, v159
	v_add_u32_e32 v167, s46, v159
	v_add_u32_e32 v168, 0, v7
	s_mov_b32 s47, 0xc0000
	v_lshlrev_b32_e32 v138, 1, v6
	v_lshlrev_b32_e32 v148, 1, v4
	v_lshlrev_b32_e32 v150, 1, v2
	v_mov_b32_e32 v169, 0x300
	v_mov_b32_e32 v170, 0x3e38aa3b
	s_barrier
	s_branch .LBB0_400

; #define PG8_STAGE(bufoff, gbase, voff) do { _Pragma("unroll") for (int _i = 0; _i < 2; ++_i) \
;         __builtin_amdgcn_global_load_lds((const unsigned*)((const char*)(gbase) + (voff)[_i]), (PG8_LAS unsigned*)(lds + (bufoff) + ldsw + _i * 8192), 16, 0, 0); } while (0)
; #define PG8_WAIT_V(n) asm volatile("s_waitcnt vmcnt(" #n ")" ::: "memory")
; #define PG8_BAR __builtin_amdgcn_s_barrier()
; template <class Epi, class Sched, bool ALIGN_EPI>
; __device__ __forceinline__ void gemm_phase(PG8_LAS unsigned char* lds, const Gemm g, const Sched& S, const Epi& E) {
;     ...
;     for (int i = 0; i < 2; ++i) { int R, C; stage_rc(tid * 16 + i * 8192, R, C); const int Rb = Epi::PERM ? ((R & ~31) + perm32(R & 31)) : R;
;         voffA[i] = g.ablk ? (unsigned)((C >> 4) * g.ablk + R * 16 + (C & 15)) * 2u : (unsigned)(R * g.lda + C) * 2u; voffB[i] = (unsigned)(Rb * g.ldb + C) * 2u; }
;     const size_t kstep = (size_t)(BK * 2), kstepA = g.ablk ? (size_t)4 * g.ablk * 2 : kstep;
;     const size_t hstepA = g.ablk ? (size_t)HALF * 16 * 2 : (size_t)HALF * g.lda * 2, hstepB = (size_t)HALF * g.ldb * 2;
;     const size_t tstepA = 2 * hstepA, tstepB = 2 * hstepB;
;     const unsigned ldsw = (unsigned)wid * 1024u;
;     const size_t tailoff = (size_t)(nt - 2) * (size_t)(BK * 2), tailoffA = (size_t)(nt - 2) * kstepA;
;     const int aoff = lds_byte(wr * 64 + fr, fq * 8), boff = lds_byte(wc * 32 + fr, fq * 8);
;     ...
;     const char* cA = (const char*)g.A + (size_t)cur.pm * tstepA; const char* cB = (const char*)g.Bt + (size_t)cur.pn * tstepB;
;     PG8_STAGE(PG8_SB(0, 0), cB, voffB); PG8_STAGE(PG8_SB(0, 1), cB + hstepB, voffB); PG8_STAGE(PG8_SA(0, 0), cA, voffA); PG8_STAGE(PG8_SA(0, 1), cA + hstepA, voffA);
;     if (wr == 1) PG8_BAR;
;     PG8_WAIT_V(2); PG8_BAR;
;     PG8_STAGE(PG8_SB(1, 0), cB + kstep, voffB); PG8_STAGE(PG8_SA(1, 0), cA + kstepA, voffA); PG8_STAGE(PG8_SB(1, 1), cB + hstepB + kstep, voffB);
;     PG8_WAIT_V(6); PG8_BAR;
.LBB0_421:
	s_lshl_b32 s6, s6, 5
	s_and_b32 s16, s6, 0x60
	s_lshl_b32 s13, s12, 13
	s_lshl_b32 s17, s16, 7
	s_add_u32 s6, s94, 0xd800000
	s_mov_b64 s[8:9], 0x80
	s_addc_u32 s7, s95, 0
	s_add_i32 m0, s29, 0x18000
	v_lshl_add_u64 v[8:9], v[8:9], 0, s[8:9]
	global_load_lds_dwordx4 v[8:9], off
	v_lshl_add_u64 v[6:7], v[6:7], 0, s[8:9]
	s_add_i32 m0, s29, 0x1a000
	s_add_i32 s44, s29, 0x8000
	s_add_i32 s45, s29, 0xa000
	global_load_lds_dwordx4 v[6:7], off
	v_lshl_add_u64 v[2:3], v[2:3], 0, s[8:9]
	s_mov_b32 m0, s44
	s_add_u32 s14, s34, 0x80080
	global_load_lds_dwordx4 v[2:3], off
	v_lshl_add_u64 v[2:3], v[4:5], 0, s[8:9]
	s_mov_b32 m0, s45
	s_addc_u32 s15, s35, 0
	global_load_lds_dwordx4 v[2:3], off
	s_add_i32 m0, s29, 0x1c000
	v_lshl_add_u64 v[2:3], s[14:15], 0, v[132:133]
	global_load_lds_dwordx4 v[2:3], off
	v_lshl_add_u64 v[2:3], s[14:15], 0, v[136:137]
	s_add_i32 m0, s29, 0x1e000
	s_cmpk_lt_u32 s11, 0x100
	global_load_lds_dwordx4 v[2:3], off
	v_lshrrev_b32_e32 v3, 1, v10
	v_and_b32_e32 v3, 24, v3
	v_and_b32_e32 v2, 15, v10
	v_lshlrev_b32_e32 v4, 1, v3
	v_lshl_or_b32 v144, s12, 6, v2
	v_lshl_or_b32 v2, v2, 6, v4
	v_lshlrev_b32_e32 v4, 2, v10
	v_and_b32_e32 v4, 32, v4
	v_bitop3_b32 v5, v2, s13, v4 bitop3:0xde
	v_bitop3_b32 v145, v2, s17, v4 bitop3:0xde
	v_lshlrev_b32_e32 v2, 15, v11
	v_and_b32_e32 v2, 0xffff0000, v2
	v_or_b32_e32 v146, s16, v3
	v_lshl_add_u32 v2, v12, 12, v2
	v_and_b32_e32 v3, 1, v11
	v_lshl_or_b32 v2, v3, 6, v2
	v_lshl_add_u32 v138, v13, 1, v2
	v_lshlrev_b32_e32 v2, 15, v14
	v_and_b32_e32 v2, 0xffff0000, v2
	s_waitcnt vmcnt(8)
	s_barrier
	s_waitcnt vmcnt(6)
	v_lshl_add_u32 v2, v15, 12, v2
	v_and_b32_e32 v3, 1, v14
	s_sext_i32_i16 s53, s10
	s_cselect_b64 s[10:11], -1, 0
	v_lshl_or_b32 v2, v3, 6, v2
	s_add_i32 s47, 0, 0x10000
	s_add_i32 s48, 0, 0x14000
	s_ashr_i32 s46, s33, 31
	v_mov_b32_e32 v139, v133
	v_lshl_add_u32 v140, v16, 1, v2
	v_mov_b32_e32 v141, v133
	v_add_u32_e32 v147, s47, v145
	v_add_u32_e32 v148, s48, v145
	v_add_u32_e32 v149, 0, v5
	s_mov_b32 s49, 0x400000
	s_mov_b64 s[12:13], 0x480000
	s_mov_b32 s50, 0x480000
	s_mov_b64 s[14:15], 0x500000
	s_mov_b32 s51, 0x500000
	s_mov_b64 s[16:17], 0x580000
	s_mov_b32 s52, 0x580000
	s_barrier
	s_branch .LBB0_424

; #define PG8_STAGE(bufoff, gbase, voff) do { _Pragma("unroll") for (int _i = 0; _i < 2; ++_i) \
;         __builtin_amdgcn_global_load_lds((const unsigned*)((const char*)(gbase) + (voff)[_i]), (PG8_LAS unsigned*)(lds + (bufoff) + ldsw + _i * 8192), 16, 0, 0); } while (0)
; #define PG8_WAIT_V(n) asm volatile("s_waitcnt vmcnt(" #n ")" ::: "memory")
; #define PG8_BAR __builtin_amdgcn_s_barrier()
; template <class Epi, class Sched, bool ALIGN_EPI>
; __device__ __forceinline__ void gemm_phase(PG8_LAS unsigned char* lds, const Gemm g, const Sched& S, const Epi& E) {
;     ...
;     for (int i = 0; i < 2; ++i) { int R, C; stage_rc(tid * 16 + i * 8192, R, C); const int Rb = Epi::PERM ? ((R & ~31) + perm32(R & 31)) : R;
;         voffA[i] = g.ablk ? (unsigned)((C >> 4) * g.ablk + R * 16 + (C & 15)) * 2u : (unsigned)(R * g.lda + C) * 2u; voffB[i] = (unsigned)(Rb * g.ldb + C) * 2u; }
;     const size_t kstep = (size_t)(BK * 2), kstepA = g.ablk ? (size_t)4 * g.ablk * 2 : kstep;
;     const size_t hstepA = g.ablk ? (size_t)HALF * 16 * 2 : (size_t)HALF * g.lda * 2, hstepB = (size_t)HALF * g.ldb * 2;
;     const size_t tstepA = 2 * hstepA, tstepB = 2 * hstepB;
;     const unsigned ldsw = (unsigned)wid * 1024u;
;     const size_t tailoff = (size_t)(nt - 2) * (size_t)(BK * 2), tailoffA = (size_t)(nt - 2) * kstepA;
;     const int aoff = lds_byte(wr * 64 + fr, fq * 8), boff = lds_byte(wc * 32 + fr, fq * 8);
;     ...
;     const char* cA = (const char*)g.A + (size_t)cur.pm * tstepA; const char* cB = (const char*)g.Bt + (size_t)cur.pn * tstepB;
;     PG8_STAGE(PG8_SB(0, 0), cB, voffB); PG8_STAGE(PG8_SB(0, 1), cB + hstepB, voffB); PG8_STAGE(PG8_SA(0, 0), cA, voffA); PG8_STAGE(PG8_SA(0, 1), cA + hstepA, voffA);
;     if (wr == 1) PG8_BAR;
;     PG8_WAIT_V(2); PG8_BAR;
;     PG8_STAGE(PG8_SB(1, 0), cB + kstep, voffB); PG8_STAGE(PG8_SA(1, 0), cA + kstepA, voffA); PG8_STAGE(PG8_SB(1, 1), cB + hstepB + kstep, voffB);
;     PG8_WAIT_V(6); PG8_BAR;
.LBB0_623:
	s_lshl_b32 s15, s12, 6
	s_lshl_b32 s18, s12, 13
	s_lshl_b32 s1, s1, 5
	s_mov_b64 s[12:13], 0x80
	s_and_b32 s1, s1, 0x60
	s_add_i32 m0, s35, 0x18000
	v_lshl_add_u64 v[8:9], v[8:9], 0, s[12:13]
	s_lshl_b32 s19, s1, 7
	global_load_lds_dwordx4 v[8:9], off
	v_lshl_add_u64 v[6:7], v[6:7], 0, s[12:13]
	s_add_i32 m0, s35, 0x1a000
	s_add_i32 s42, s35, 0x8000
	s_add_i32 s43, s35, 0xa000
	global_load_lds_dwordx4 v[6:7], off
	v_lshl_add_u64 v[2:3], v[2:3], 0, s[12:13]
	s_mov_b32 m0, s42
	s_add_u32 s16, s28, 0x10080
	global_load_lds_dwordx4 v[2:3], off
	v_lshl_add_u64 v[2:3], v[4:5], 0, s[12:13]
	s_mov_b32 m0, s43
	s_addc_u32 s17, s29, 0
	s_add_i32 s44, s35, 0x1c000
	global_load_lds_dwordx4 v[2:3], off
	v_lshl_add_u64 v[2:3], s[16:17], 0, v[70:71]
	s_mov_b32 m0, s44
	s_add_i32 s45, s35, 0x1e000
	global_load_lds_dwordx4 v[2:3], off
	v_lshl_add_u64 v[2:3], s[16:17], 0, v[66:67]
	s_mov_b32 m0, s45
	v_and_b32_e32 v4, 15, v10
	global_load_lds_dwordx4 v[2:3], off
	v_and_b32_e32 v2, 48, v10
	v_lshlrev_b32_e32 v5, 2, v10
	s_cmpk_lt_u32 s14, 0x100
	v_lshl_or_b32 v3, v4, 6, v2
	v_and_b32_e32 v5, 32, v5
	s_cselect_b64 s[20:21], -1, 0
	v_lshl_or_b32 v2, s1, 2, v2
	s_lshl_b32 s1, s2, 8
	s_add_i32 s48, s2, s33
	v_bitop3_b32 v6, v3, s18, v5 bitop3:0xde
	v_bitop3_b32 v5, v3, s19, v5 bitop3:0xde
	v_mov_b32_e32 v3, v71
	s_add_i32 s1, s1, s15
	s_lshl_b32 s46, s33, 8
	s_mul_i32 s14, s48, 0x30000
	v_lshl_add_u64 v[74:75], s[8:9], 0, v[2:3]
	v_or_b32_e32 v2, s1, v4
	s_mul_hi_i32 s1, s48, 0x30000
	s_add_u32 s14, s94, s14
	s_addc_u32 s1, s95, s1
	s_add_u32 s14, s14, 0x15000000
	s_waitcnt vmcnt(8)
	s_barrier
	s_waitcnt vmcnt(6)
	s_addc_u32 s15, s1, 0
	s_add_i32 s50, 0, 0x10000
	s_add_i32 s52, 0, 0x18000
	v_add_u32_e32 v76, 0xb0, v2
	v_add_u32_e32 v79, s50, v5
	s_add_i32 s50, s50, s0
	v_cndmask_b32_e64 v2, 0, 1, s[20:21]
	v_add_u32_e32 v81, s52, v5
	s_add_i32 s52, s52, s0
	v_add_u32_e32 v80, 0, v6
	s_add_i32 s47, s35, 0xc000
	s_add_i32 s49, s35, 0xe000
	s_mov_b64 s[16:17], 0x100
	s_add_i32 s51, s50, 0x2000
	s_mov_b64 s[18:19], 0x180
	s_add_i32 s53, s52, 0x2000
	v_cmp_ne_u32_e64 s[0:1], 1, v2
	s_barrier
	s_branch .LBB0_626

; #define PG8_STAGE(bufoff, gbase, voff) do { _Pragma("unroll") for (int _i = 0; _i < 2; ++_i) \
;         __builtin_amdgcn_global_load_lds((const unsigned*)((const char*)(gbase) + (voff)[_i]), (PG8_LAS unsigned*)(lds + (bufoff) + ldsw + _i * 8192), 16, 0, 0); } while (0)
; #define PG8_WAIT_V(n) asm volatile("s_waitcnt vmcnt(" #n ")" ::: "memory")
; #define PG8_BAR __builtin_amdgcn_s_barrier()
; template <class Epi, class Sched, bool ALIGN_EPI>
; __device__ __forceinline__ void gemm_phase(PG8_LAS unsigned char* lds, const Gemm g, const Sched& S, const Epi& E) {
;     ...
;     for (int i = 0; i < 2; ++i) { int R, C; stage_rc(tid * 16 + i * 8192, R, C); const int Rb = Epi::PERM ? ((R & ~31) + perm32(R & 31)) : R;
;         voffA[i] = g.ablk ? (unsigned)((C >> 4) * g.ablk + R * 16 + (C & 15)) * 2u : (unsigned)(R * g.lda + C) * 2u; voffB[i] = (unsigned)(Rb * g.ldb + C) * 2u; }
;     const size_t kstep = (size_t)(BK * 2), kstepA = g.ablk ? (size_t)4 * g.ablk * 2 : kstep;
;     const size_t hstepA = g.ablk ? (size_t)HALF * 16 * 2 : (size_t)HALF * g.lda * 2, hstepB = (size_t)HALF * g.ldb * 2;
;     const size_t tstepA = 2 * hstepA, tstepB = 2 * hstepB;
;     const unsigned ldsw = (unsigned)wid * 1024u;
;     const size_t tailoff = (size_t)(nt - 2) * (size_t)(BK * 2), tailoffA = (size_t)(nt - 2) * kstepA;
;     const int aoff = lds_byte(wr * 64 + fr, fq * 8), boff = lds_byte(wc * 32 + fr, fq * 8);
;     ...
;     const char* cA = (const char*)g.A + (size_t)cur.pm * tstepA; const char* cB = (const char*)g.Bt + (size_t)cur.pn * tstepB;
;     PG8_STAGE(PG8_SB(0, 0), cB, voffB); PG8_STAGE(PG8_SB(0, 1), cB + hstepB, voffB); PG8_STAGE(PG8_SA(0, 0), cA, voffA); PG8_STAGE(PG8_SA(0, 1), cA + hstepA, voffA);
;     if (wr == 1) PG8_BAR;
;     PG8_WAIT_V(2); PG8_BAR;
;     PG8_STAGE(PG8_SB(1, 0), cB + kstep, voffB); PG8_STAGE(PG8_SA(1, 0), cA + kstepA, voffA); PG8_STAGE(PG8_SB(1, 1), cB + hstepB + kstep, voffB);
;     PG8_WAIT_V(6); PG8_BAR;
.LBB0_641:
	s_and_b32 s7, s10, 3
	s_mov_b64 s[10:11], 0x80
	s_add_i32 m0, s42, 0x18000
	v_lshl_add_u64 v[10:11], v[10:11], 0, s[10:11]
	s_lshl_b32 s12, s1, 13
	s_lshl_b32 s13, s7, 12
	global_load_lds_dwordx4 v[10:11], off
	v_lshl_add_u64 v[8:9], v[8:9], 0, s[10:11]
	s_add_i32 m0, s42, 0x1a000
	s_add_i32 s47, s42, 0x8000
	s_add_i32 s48, s42, 0xa000
	global_load_lds_dwordx4 v[8:9], off
	v_lshl_add_u64 v[6:7], v[6:7], 0, s[10:11]
	s_mov_b32 m0, s47
	s_add_u32 s4, s30, 0x18080
	global_load_lds_dwordx4 v[6:7], off
	v_lshl_add_u64 v[4:5], v[4:5], 0, s[10:11]
	s_mov_b32 m0, s48
	s_addc_u32 s5, s31, 0
	global_load_lds_dwordx4 v[4:5], off
	s_add_i32 m0, s42, 0x1c000
	v_lshl_add_u64 v[4:5], s[4:5], 0, v[136:137]
	global_load_lds_dwordx4 v[4:5], off
	v_lshl_add_u64 v[4:5], s[4:5], 0, v[132:133]
	s_add_i32 m0, s42, 0x1e000
	v_bfe_u32 v6, v3, 4, 2
	global_load_lds_dwordx4 v[4:5], off
	v_and_b32_e32 v5, 15, v3
	v_lshrrev_b32_e32 v4, 4, v3
	v_lshrrev_b32_e32 v7, 1, v3
	v_lshlrev_b32_e32 v8, 6, v5
	v_lshlrev_b32_e32 v3, 2, v3
	v_lshl_or_b32 v6, v6, 4, v8
	v_and_b32_e32 v3, 32, v3
	s_cmpk_lt_u32 s0, 0x100
	v_bitop3_b32 v8, v6, s12, v3 bitop3:0xde
	v_bitop3_b32 v6, v6, s13, v3 bitop3:0xde
	s_cselect_b64 s[12:13], -1, 0
	s_lshl_b32 s0, s2, 12
	s_lshl_b32 s1, s1, 10
	s_add_i32 s50, s2, s33
	s_add_i32 s0, s0, s1
	s_lshl_b32 s49, s33, 12
	s_mul_i32 s1, s50, 0x30000
	v_lshl_or_b32 v145, v5, 4, s0
	s_mul_hi_i32 s0, s50, 0x30000
	s_add_u32 s1, s94, s1
	s_addc_u32 s0, s95, s0
	s_add_u32 s14, s1, 0x15000000
	s_waitcnt vmcnt(8)
	s_barrier
	s_waitcnt vmcnt(6)
	v_bfe_u32 v4, v4, 1, 1
	s_addc_u32 s15, s0, 0
	s_add_i32 s53, 0, 0x10000
	s_add_i32 s58, 0, 0x14000
	v_lshl_or_b32 v144, s7, 1, v4
	v_and_b32_e32 v4, 8, v7
	v_add_u32_e32 v146, s53, v6
	v_add_u32_e32 v147, s58, v6
	s_add_i32 s53, s53, s41
	s_add_i32 s58, s58, s41
	s_add_i32 s61, 0, 0x18000
	s_add_i32 s60, 0, 0x1c000
	v_add_u32_e32 v3, 0, v8
	s_add_i32 s51, s42, 0xc000
	s_add_i32 s52, s42, 0xe000
	s_mov_b64 s[16:17], 0x100
	s_movk_i32 s54, 0x2000
	s_movk_i32 s55, 0x4000
	s_mov_b64 s[18:19], 0x180
	s_mov_b64 s[20:21], 0x200
	s_mov_b64 s[22:23], 0x280
	s_movk_i32 s56, 0x3cf0
	v_lshlrev_b32_e32 v142, 1, v4
	s_add_i32 s57, s53, 0x2000
	s_add_i32 s59, s58, 0x2000
	v_add_u32_e32 v148, s61, v6
	v_add_u32_e32 v149, s60, v6
	s_add_i32 s61, s61, s41
	s_barrier
	s_branch .LBB0_644

; #define PG8_STAGE(bufoff, gbase, voff) do { _Pragma("unroll") for (int _i = 0; _i < 2; ++_i) \
;         __builtin_amdgcn_global_load_lds((const unsigned*)((const char*)(gbase) + (voff)[_i]), (PG8_LAS unsigned*)(lds + (bufoff) + ldsw + _i * 8192), 16, 0, 0); } while (0)
; #define PG8_WAIT_V(n) asm volatile("s_waitcnt vmcnt(" #n ")" ::: "memory")
; #define PG8_BAR __builtin_amdgcn_s_barrier()
; template <class Epi, class Sched, bool ALIGN_EPI>
; __device__ __forceinline__ void gemm_phase(PG8_LAS unsigned char* lds, const Gemm g, const Sched& S, const Epi& E) {
;     ...
;     for (int i = 0; i < 2; ++i) { int R, C; stage_rc(tid * 16 + i * 8192, R, C); const int Rb = Epi::PERM ? ((R & ~31) + perm32(R & 31)) : R;
;         voffA[i] = g.ablk ? (unsigned)((C >> 4) * g.ablk + R * 16 + (C & 15)) * 2u : (unsigned)(R * g.lda + C) * 2u; voffB[i] = (unsigned)(Rb * g.ldb + C) * 2u; }
;     const size_t kstep = (size_t)(BK * 2), kstepA = g.ablk ? (size_t)4 * g.ablk * 2 : kstep;
;     const size_t hstepA = g.ablk ? (size_t)HALF * 16 * 2 : (size_t)HALF * g.lda * 2, hstepB = (size_t)HALF * g.ldb * 2;
;     const size_t tstepA = 2 * hstepA, tstepB = 2 * hstepB;
;     const unsigned ldsw = (unsigned)wid * 1024u;
;     const size_t tailoff = (size_t)(nt - 2) * (size_t)(BK * 2), tailoffA = (size_t)(nt - 2) * kstepA;
;     const int aoff = lds_byte(wr * 64 + fr, fq * 8), boff = lds_byte(wc * 32 + fr, fq * 8);
;     ...
;     const char* cA = (const char*)g.A + (size_t)cur.pm * tstepA; const char* cB = (const char*)g.Bt + (size_t)cur.pn * tstepB;
;     PG8_STAGE(PG8_SB(0, 0), cB, voffB); PG8_STAGE(PG8_SB(0, 1), cB + hstepB, voffB); PG8_STAGE(PG8_SA(0, 0), cA, voffA); PG8_STAGE(PG8_SA(0, 1), cA + hstepA, voffA);
;     if (wr == 1) PG8_BAR;
;     PG8_WAIT_V(2); PG8_BAR;
;     PG8_STAGE(PG8_SB(1, 0), cB + kstep, voffB); PG8_STAGE(PG8_SA(1, 0), cA + kstepA, voffA); PG8_STAGE(PG8_SB(1, 1), cB + hstepB + kstep, voffB);
;     PG8_WAIT_V(6); PG8_BAR;
.LBB0_767:
	s_add_u32 s10, s94, 0xf000800
	s_addc_u32 s11, s95, 0
	s_lshl_b32 s1, s1, 5
	s_mov_b64 s[16:17], 0x80
	s_and_b32 s5, s1, 0x60
	s_add_i32 m0, s31, 0x18000
	v_lshl_add_u64 v[4:5], v[4:5], 0, s[16:17]
	s_lshl_b32 s2, s0, 13
	s_lshl_b32 s1, s5, 7
	global_load_lds_dwordx4 v[4:5], off
	s_add_i32 m0, s31, 0x1a000
	s_add_u32 s6, s34, 0x200000
	v_lshl_add_u64 v[2:3], v[2:3], 0, s[16:17]
	s_addc_u32 s7, s35, 0
	s_add_i32 s48, s31, 0x8000
	global_load_lds_dwordx4 v[2:3], off
	v_lshl_add_u64 v[2:3], s[6:7], 0, v[138:139]
	s_mov_b32 m0, s48
	s_add_i32 s49, s31, 0xa000
	global_load_lds_dwordx4 v[2:3], off
	v_lshl_add_u64 v[2:3], s[6:7], 0, v[142:143]
	s_add_u32 s6, s36, 0x40080
	s_mov_b32 m0, s49
	s_addc_u32 s7, s37, 0
	global_load_lds_dwordx4 v[2:3], off
	s_add_i32 m0, s31, 0x1c000
	v_lshl_add_u64 v[2:3], s[6:7], 0, v[140:141]
	global_load_lds_dwordx4 v[2:3], off
	v_lshl_add_u64 v[2:3], s[6:7], 0, v[144:145]
	s_add_i32 m0, s31, 0x1e000
	s_cmpk_lt_u32 s4, 0x100
	global_load_lds_dwordx4 v[2:3], off
	v_bfe_u32 v3, v6, 4, 2
	v_and_b32_e32 v2, 15, v6
	v_lshlrev_b32_e32 v5, 4, v3
	v_lshl_or_b32 v174, s0, 6, v2
	v_lshl_or_b32 v2, v2, 6, v5
	v_lshlrev_b32_e32 v5, 2, v6
	v_and_b32_e32 v5, 32, v5
	v_lshlrev_b32_e32 v4, 3, v3
	v_bitop3_b32 v175, v2, s1, v5 bitop3:0xde
	v_cmp_eq_u32_e64 s[0:1], 0, v3
	v_xor_b32_e32 v3, 16, v1
	v_cmp_lt_i32_e32 vcc, v3, v173
	v_bitop3_b32 v6, v2, s2, v5 bitop3:0xde
	v_and_b32_e32 v2, 8, v4
	v_cndmask_b32_e32 v3, v1, v3, vcc
	v_lshlrev_b32_e32 v176, 2, v3
	v_lshlrev_b32_e32 v3, 7, v7
	v_or_b32_e32 v177, s5, v4
	v_and_b32_e32 v3, 0x7fffff00, v3
	v_lshlrev_b32_e32 v4, 4, v8
	v_add3_u32 v3, v9, v3, v4
	v_add_lshl_u32 v146, v3, v10, 1
	v_lshlrev_b32_e32 v3, 7, v11
	v_and_b32_e32 v3, 0x7fffff00, v3
	v_lshlrev_b32_e32 v4, 4, v12
	s_waitcnt vmcnt(8)
	s_barrier
	s_waitcnt vmcnt(6)
	s_mov_b64 s[4:5], 0x201000
	v_add3_u32 v3, v13, v3, v4
	s_cselect_b64 s[18:19], -1, 0
	v_lshl_add_u64 v[148:149], v[146:147], 0, s[4:5]
	v_add_lshl_u32 v146, v3, v14, 1
	s_add_i32 s52, 0, 0x10000
	s_add_i32 s53, 0, 0x14000
	s_ashr_i32 s50, s33, 31
	s_ashr_i32 s51, s74, 31
	v_lshl_add_u64 v[150:151], v[146:147], 0, s[4:5]
	v_mov_b64_e32 v[152:153], 0x100
	v_mov_b64_e32 v[154:155], 0xff
	v_add_u32_e32 v178, s52, v175
	v_add_u32_e32 v179, s53, v175
	v_add_u32_e32 v180, 0, v6
	v_lshlrev_b32_e32 v146, 1, v2
	s_barrier
	s_branch .LBB0_770

; #define PG8_STAGE(bufoff, gbase, voff) do { _Pragma("unroll") for (int _i = 0; _i < 2; ++_i) \
;         __builtin_amdgcn_global_load_lds((const unsigned*)((const char*)(gbase) + (voff)[_i]), (PG8_LAS unsigned*)(lds + (bufoff) + ldsw + _i * 8192), 16, 0, 0); } while (0)
; #define PG8_WAIT_V(n) asm volatile("s_waitcnt vmcnt(" #n ")" ::: "memory")
; #define PG8_BAR __builtin_amdgcn_s_barrier()
; template <class Epi, class Sched, bool ALIGN_EPI>
; __device__ __forceinline__ void gemm_phase(PG8_LAS unsigned char* lds, const Gemm g, const Sched& S, const Epi& E) {
;     ...
;     for (int i = 0; i < 2; ++i) { int R, C; stage_rc(tid * 16 + i * 8192, R, C); const int Rb = Epi::PERM ? ((R & ~31) + perm32(R & 31)) : R;
;         voffA[i] = g.ablk ? (unsigned)((C >> 4) * g.ablk + R * 16 + (C & 15)) * 2u : (unsigned)(R * g.lda + C) * 2u; voffB[i] = (unsigned)(Rb * g.ldb + C) * 2u; }
;     const size_t kstep = (size_t)(BK * 2), kstepA = g.ablk ? (size_t)4 * g.ablk * 2 : kstep;
;     const size_t hstepA = g.ablk ? (size_t)HALF * 16 * 2 : (size_t)HALF * g.lda * 2, hstepB = (size_t)HALF * g.ldb * 2;
;     const size_t tstepA = 2 * hstepA, tstepB = 2 * hstepB;
;     const unsigned ldsw = (unsigned)wid * 1024u;
;     const size_t tailoff = (size_t)(nt - 2) * (size_t)(BK * 2), tailoffA = (size_t)(nt - 2) * kstepA;
;     const int aoff = lds_byte(wr * 64 + fr, fq * 8), boff = lds_byte(wc * 32 + fr, fq * 8);
;     ...
;     const char* cA = (const char*)g.A + (size_t)cur.pm * tstepA; const char* cB = (const char*)g.Bt + (size_t)cur.pn * tstepB;
;     PG8_STAGE(PG8_SB(0, 0), cB, voffB); PG8_STAGE(PG8_SB(0, 1), cB + hstepB, voffB); PG8_STAGE(PG8_SA(0, 0), cA, voffA); PG8_STAGE(PG8_SA(0, 1), cA + hstepA, voffA);
;     if (wr == 1) PG8_BAR;
;     PG8_WAIT_V(2); PG8_BAR;
;     PG8_STAGE(PG8_SB(1, 0), cB + kstep, voffB); PG8_STAGE(PG8_SA(1, 0), cA + kstepA, voffA); PG8_STAGE(PG8_SB(1, 1), cB + hstepB + kstep, voffB);
;     PG8_WAIT_V(6); PG8_BAR;
.LBB0_829:
	s_lshl_b32 s16, s16, 5
	s_and_b32 s22, s16, 0x60
	s_mov_b64 s[16:17], 0x80
	s_add_i32 m0, s37, 0x18000
	v_lshl_add_u64 v[10:11], v[10:11], 0, s[16:17]
	s_lshl_b32 s2, s1, 13
	s_lshl_b32 s19, s22, 7
	global_load_lds_dwordx4 v[10:11], off
	v_lshl_add_u64 v[6:7], v[6:7], 0, s[16:17]
	s_add_i32 m0, s37, 0x1a000
	s_add_i32 s52, s37, 0x8000
	s_add_i32 s53, s37, 0xa000
	global_load_lds_dwordx4 v[6:7], off
	v_lshl_add_u64 v[4:5], v[4:5], 0, s[16:17]
	s_mov_b32 m0, s52
	s_add_u32 s20, s40, 0x80080
	global_load_lds_dwordx4 v[4:5], off
	v_lshl_add_u64 v[4:5], v[8:9], 0, s[16:17]
	s_mov_b32 m0, s53
	s_addc_u32 s21, s41, 0
	global_load_lds_dwordx4 v[4:5], off
	s_add_i32 m0, s37, 0x1c000
	v_lshl_add_u64 v[4:5], s[20:21], 0, v[136:137]
	global_load_lds_dwordx4 v[4:5], off
	v_lshl_add_u64 v[4:5], s[20:21], 0, v[140:141]
	s_add_i32 m0, s37, 0x1e000
	s_sext_i32_i8 s61, s0
	global_load_lds_dwordx4 v[4:5], off
	v_and_b32_e32 v4, 15, v3
	v_lshrrev_b32_e32 v3, 1, v3
	v_and_b32_e32 v3, 24, v3
	v_lshlrev_b32_e32 v5, 1, v3
	v_lshl_or_b32 v154, s1, 6, v4
	v_lshl_or_b32 v5, v4, 6, v5
	v_lshlrev_b32_e32 v4, 2, v4
	s_and_b32 s0, s18, 0xffffff00
	v_and_b32_e32 v6, 32, v4
	s_cmpk_lt_u32 s18, 0x100
	v_bitop3_b32 v155, v5, s19, v6 bitop3:0xde
	s_cselect_b64 s[18:19], -1, 0
	s_add_i32 s0, s0, 0
	s_add_i32 s0, s0, 0x20800
	v_add_u32_e32 v156, s0, v4
	s_lshl_b32 s0, s1, 8
	s_add_i32 s0, s0, 0
	v_or_b32_e32 v158, s22, v3
	v_lshlrev_b32_e32 v3, 15, v12
	s_add_i32 s0, s0, 0x20c00
	v_and_b32_e32 v3, 0xffff0000, v3
	v_add_u32_e32 v157, s0, v4
	v_lshl_add_u32 v3, v13, 12, v3
	v_and_b32_e32 v4, 1, v12
	v_lshl_or_b32 v3, v4, 6, v3
	v_lshl_add_u32 v4, v14, 1, v3
	v_lshlrev_b32_e32 v3, 15, v15
	v_bitop3_b32 v7, v5, s2, v6 bitop3:0xde
	s_mov_b64 s[20:21], 0x80080
	v_mov_b32_e32 v5, v2
	v_and_b32_e32 v3, 0xffff0000, v3
	v_lshl_add_u64 v[142:143], v[4:5], 0, s[20:21]
	v_lshl_add_u32 v3, v16, 12, v3
	v_and_b32_e32 v4, 1, v15
	s_waitcnt vmcnt(8)
	s_barrier
	s_waitcnt vmcnt(6)
	v_lshl_or_b32 v3, v4, 6, v3
	v_lshl_add_u32 v4, v17, 1, v3
	s_ashr_i32 s54, s33, 31
	v_lshl_add_u64 v[144:145], v[4:5], 0, s[20:21]
	v_mov_b64_e32 v[146:147], 0x200
	v_mov_b64_e32 v[148:149], 0x1ff
	s_add_i32 s55, 0, 0x10000
	s_add_i32 s56, 0, 0x14000
	v_add_u32_e32 v159, 0, v7
	s_mov_b32 s57, 0x80000
	s_mov_b64 s[20:21], 0x90000
	s_mov_b32 s58, 0x90000
	s_mov_b64 s[22:23], 0xa0000
	s_mov_b32 s59, 0xa0000
	s_mov_b64 s[24:25], 0xb0000
	s_mov_b32 s60, 0xb0000
	s_barrier
	s_branch .LBB0_832

; #define PG8_STAGE(bufoff, gbase, voff) do { _Pragma("unroll") for (int _i = 0; _i < 2; ++_i) \
;         __builtin_amdgcn_global_load_lds((const unsigned*)((const char*)(gbase) + (voff)[_i]), (PG8_LAS unsigned*)(lds + (bufoff) + ldsw + _i * 8192), 16, 0, 0); } while (0)
; #define PG8_WAIT_V(n) asm volatile("s_waitcnt vmcnt(" #n ")" ::: "memory")
; #define PG8_BAR __builtin_amdgcn_s_barrier()
; template <class Epi, class Sched, bool ALIGN_EPI>
; __device__ __forceinline__ void gemm_phase(PG8_LAS unsigned char* lds, const Gemm g, const Sched& S, const Epi& E) {
;     ...
;     for (int i = 0; i < 2; ++i) { int R, C; stage_rc(tid * 16 + i * 8192, R, C); const int Rb = Epi::PERM ? ((R & ~31) + perm32(R & 31)) : R;
;         voffA[i] = g.ablk ? (unsigned)((C >> 4) * g.ablk + R * 16 + (C & 15)) * 2u : (unsigned)(R * g.lda + C) * 2u; voffB[i] = (unsigned)(Rb * g.ldb + C) * 2u; }
;     const size_t kstep = (size_t)(BK * 2), kstepA = g.ablk ? (size_t)4 * g.ablk * 2 : kstep;
;     const size_t hstepA = g.ablk ? (size_t)HALF * 16 * 2 : (size_t)HALF * g.lda * 2, hstepB = (size_t)HALF * g.ldb * 2;
;     const size_t tstepA = 2 * hstepA, tstepB = 2 * hstepB;
;     const unsigned ldsw = (unsigned)wid * 1024u;
;     const size_t tailoff = (size_t)(nt - 2) * (size_t)(BK * 2), tailoffA = (size_t)(nt - 2) * kstepA;
;     const int aoff = lds_byte(wr * 64 + fr, fq * 8), boff = lds_byte(wc * 32 + fr, fq * 8);
;     ...
;     const char* cA = (const char*)g.A + (size_t)cur.pm * tstepA; const char* cB = (const char*)g.Bt + (size_t)cur.pn * tstepB;
;     PG8_STAGE(PG8_SB(0, 0), cB, voffB); PG8_STAGE(PG8_SB(0, 1), cB + hstepB, voffB); PG8_STAGE(PG8_SA(0, 0), cA, voffA); PG8_STAGE(PG8_SA(0, 1), cA + hstepA, voffA);
;     if (wr == 1) PG8_BAR;
;     PG8_WAIT_V(2); PG8_BAR;
;     PG8_STAGE(PG8_SB(1, 0), cB + kstep, voffB); PG8_STAGE(PG8_SA(1, 0), cA + kstepA, voffA); PG8_STAGE(PG8_SB(1, 1), cB + hstepB + kstep, voffB);
;     PG8_WAIT_V(6); PG8_BAR;
.LBB0_895:
	s_lshl_b32 s5, s5, 5
	s_mov_b64 s[14:15], 0x80
	s_and_b32 s5, s5, 0x60
	s_add_i32 m0, s27, 0x18000
	v_lshl_add_u64 v[8:9], v[8:9], 0, s[14:15]
	s_lshl_b32 s2, s4, 13
	s_lshl_b32 s18, s5, 7
	global_load_lds_dwordx4 v[8:9], off
	v_lshl_add_u64 v[6:7], v[6:7], 0, s[14:15]
	s_add_i32 m0, s27, 0x1a000
	s_add_i32 s43, s27, 0x8000
	s_add_i32 s44, s27, 0xa000
	global_load_lds_dwordx4 v[6:7], off
	v_lshl_add_u64 v[2:3], v[2:3], 0, s[14:15]
	s_mov_b32 m0, s43
	s_add_u32 s16, s30, 0x80080
	global_load_lds_dwordx4 v[2:3], off
	v_lshl_add_u64 v[2:3], v[4:5], 0, s[14:15]
	s_mov_b32 m0, s44
	s_addc_u32 s17, s31, 0
	global_load_lds_dwordx4 v[2:3], off
	s_add_i32 m0, s27, 0x1c000
	v_lshl_add_u64 v[2:3], s[16:17], 0, v[134:135]
	global_load_lds_dwordx4 v[2:3], off
	v_lshl_add_u64 v[2:3], s[16:17], 0, v[130:131]
	s_add_i32 m0, s27, 0x1e000
	s_cmpk_lt_u32 s1, 0x100
	global_load_lds_dwordx4 v[2:3], off
	v_lshrrev_b32_e32 v3, 1, v12
	v_and_b32_e32 v3, 24, v3
	v_and_b32_e32 v2, 15, v12
	v_lshlrev_b32_e32 v4, 1, v3
	v_lshl_or_b32 v1, s4, 6, v2
	v_lshl_or_b32 v2, v2, 6, v4
	v_lshlrev_b32_e32 v4, 2, v12
	v_and_b32_e32 v4, 32, v4
	v_bitop3_b32 v5, v2, s2, v4 bitop3:0xde
	v_bitop3_b32 v146, v2, s18, v4 bitop3:0xde
	v_lshlrev_b32_e32 v2, 15, v15
	v_and_b32_e32 v2, 0xffff0000, v2
	v_or_b32_e32 v147, s5, v3
	v_lshl_add_u32 v2, v14, 12, v2
	v_and_b32_e32 v3, 1, v15
	v_lshl_or_b32 v2, v3, 6, v2
	v_lshl_add_u32 v138, v16, 1, v2
	v_lshlrev_b32_e32 v2, 15, v10
	v_and_b32_e32 v2, 0xffff0000, v2
	s_waitcnt vmcnt(6)
	s_barrier
	s_waitcnt vmcnt(6)
	v_lshl_add_u32 v2, v11, 12, v2
	v_and_b32_e32 v3, 1, v10
	s_cselect_b64 s[16:17], -1, 0
	v_lshl_or_b32 v2, v3, 6, v2
	s_add_i32 s5, 0, 0x10000
	s_add_i32 s45, 0, 0x14000
	s_sext_i32_i16 s48, s0
	s_ashr_i32 s4, s33, 31
	v_mov_b32_e32 v139, v135
	v_lshl_add_u32 v140, v13, 1, v2
	v_mov_b32_e32 v141, v135
	v_mov_b64_e32 v[142:143], 0xb00
	v_mov_b64_e32 v[144:145], 0xaff
	v_add_u32_e32 v153, s5, v146
	v_add_u32_e32 v154, s45, v146
	v_add_u32_e32 v155, 0, v5
	s_movk_i32 s47, 0x2c00
	s_add_u32 s50, s28, 0x80080
	s_addc_u32 s51, s29, 0
	s_add_i32 m0, s27, 0xc000
	s_nop 0
	global_load_lds_dwordx4 v136, s[50:51]
	s_barrier
	s_branch .LBB0_898

; #define PG8_STAGE(bufoff, gbase, voff) do { _Pragma("unroll") for (int _i = 0; _i < 2; ++_i) \
;         __builtin_amdgcn_global_load_lds((const unsigned*)((const char*)(gbase) + (voff)[_i]), (PG8_LAS unsigned*)(lds + (bufoff) + ldsw + _i * 8192), 16, 0, 0); } while (0)
; #define PG8_WAIT_V(n) asm volatile("s_waitcnt vmcnt(" #n ")" ::: "memory")
; #define PG8_BAR __builtin_amdgcn_s_barrier()
; template <class Epi, class Sched, bool ALIGN_EPI>
; __device__ __forceinline__ void gemm_phase(PG8_LAS unsigned char* lds, const Gemm g, const Sched& S, const Epi& E) {
;     ...
;     for (int i = 0; i < 2; ++i) { int R, C; stage_rc(tid * 16 + i * 8192, R, C); const int Rb = Epi::PERM ? ((R & ~31) + perm32(R & 31)) : R;
;         voffA[i] = g.ablk ? (unsigned)((C >> 4) * g.ablk + R * 16 + (C & 15)) * 2u : (unsigned)(R * g.lda + C) * 2u; voffB[i] = (unsigned)(Rb * g.ldb + C) * 2u; }
;     const size_t kstep = (size_t)(BK * 2), kstepA = g.ablk ? (size_t)4 * g.ablk * 2 : kstep;
;     const size_t hstepA = g.ablk ? (size_t)HALF * 16 * 2 : (size_t)HALF * g.lda * 2, hstepB = (size_t)HALF * g.ldb * 2;
;     const size_t tstepA = 2 * hstepA, tstepB = 2 * hstepB;
;     const unsigned ldsw = (unsigned)wid * 1024u;
;     const size_t tailoff = (size_t)(nt - 2) * (size_t)(BK * 2), tailoffA = (size_t)(nt - 2) * kstepA;
;     const int aoff = lds_byte(wr * 64 + fr, fq * 8), boff = lds_byte(wc * 32 + fr, fq * 8);
;     ...
;     const char* cA = (const char*)g.A + (size_t)cur.pm * tstepA; const char* cB = (const char*)g.Bt + (size_t)cur.pn * tstepB;
;     PG8_STAGE(PG8_SB(0, 0), cB, voffB); PG8_STAGE(PG8_SB(0, 1), cB + hstepB, voffB); PG8_STAGE(PG8_SA(0, 0), cA, voffA); PG8_STAGE(PG8_SA(0, 1), cA + hstepA, voffA);
;     if (wr == 1) PG8_BAR;
;     PG8_WAIT_V(2); PG8_BAR;
;     PG8_STAGE(PG8_SB(1, 0), cB + kstep, voffB); PG8_STAGE(PG8_SA(1, 0), cA + kstepA, voffA); PG8_STAGE(PG8_SB(1, 1), cB + hstepB + kstep, voffB);
;     PG8_WAIT_V(6); PG8_BAR;
.LBB0_934:
	s_lshl_b32 s1, s1, 5
	s_mov_b64 s[12:13], 0x80
	s_and_b32 s1, s1, 0x60
	s_add_i32 m0, s37, 0x18000
	v_lshl_add_u64 v[8:9], v[8:9], 0, s[12:13]
	s_lshl_b32 s2, s7, 13
	s_lshl_b32 s15, s1, 7
	global_load_lds_dwordx4 v[8:9], off
	v_lshl_add_u64 v[4:5], v[4:5], 0, s[12:13]
	s_add_i32 m0, s37, 0x1a000
	s_add_i32 s43, s37, 0x8000
	s_add_i32 s44, s37, 0xa000
	global_load_lds_dwordx4 v[4:5], off
	v_lshl_add_u64 v[2:3], v[2:3], 0, s[12:13]
	s_mov_b32 m0, s43
	s_add_u32 s18, s28, 0x160080
	global_load_lds_dwordx4 v[2:3], off
	v_lshl_add_u64 v[2:3], v[6:7], 0, s[12:13]
	s_mov_b32 m0, s44
	s_addc_u32 s19, s29, 0
	global_load_lds_dwordx4 v[2:3], off
	s_add_i32 m0, s37, 0x1c000
	v_lshl_add_u64 v[2:3], s[18:19], 0, v[132:133]
	global_load_lds_dwordx4 v[2:3], off
	v_lshl_add_u64 v[2:3], s[18:19], 0, v[136:137]
	s_add_i32 m0, s37, 0x1e000
	s_cmpk_lt_u32 s6, 0x100
	global_load_lds_dwordx4 v[2:3], off
	v_lshrrev_b32_e32 v3, 1, v10
	v_and_b32_e32 v3, 24, v3
	v_and_b32_e32 v2, 15, v10
	v_lshlrev_b32_e32 v4, 1, v3
	v_lshl_or_b32 v1, s7, 6, v2
	v_lshl_or_b32 v2, v2, 6, v4
	v_lshlrev_b32_e32 v4, 2, v10
	v_and_b32_e32 v4, 32, v4
	v_bitop3_b32 v5, v2, s2, v4 bitop3:0xde
	v_bitop3_b32 v153, v2, s15, v4 bitop3:0xde
	v_or_b32_e32 v154, s1, v3
	v_lshrrev_b32_e32 v3, 1, v11
	v_mul_lo_u32 v2, v12, s0
	v_mad_u64_u32 v[2:3], s[6:7], v3, s16, v[2:3]
	v_or_b32_e32 v2, v2, v13
	s_mov_b64 s[18:19], 0x160080
	v_add_lshl_u32 v2, v2, v14, 1
	v_mov_b32_e32 v3, v133
	v_lshl_add_u64 v[138:139], v[2:3], 0, s[18:19]
	v_lshrrev_b32_e32 v3, 1, v15
	v_mul_lo_u32 v2, v16, s0
	v_mad_u64_u32 v[2:3], s[0:1], v3, s16, v[2:3]
	s_waitcnt vmcnt(6)
	s_barrier
	s_waitcnt vmcnt(6)
	v_or_b32_e32 v2, v2, v17
	s_sext_i32_i8 s56, s14
	s_cselect_b64 s[14:15], -1, 0
	v_add_lshl_u32 v2, v2, v18, 1
	v_mov_b32_e32 v3, v133
	s_add_i32 s47, 0, 0x10000
	s_add_i32 s48, 0, 0x14000
	s_ashr_i32 s45, s33, 31
	v_lshl_add_u64 v[140:141], v[2:3], 0, s[18:19]
	v_mov_b64_e32 v[142:143], 0x200
	v_mov_b64_e32 v[144:145], 0x1ff
	v_add_u32_e32 v155, s47, v153
	v_add_u32_e32 v156, s48, v153
	v_add_u32_e32 v157, 0, v5
	s_mov_b64 s[16:17], 0x80000
	s_mov_b32 s49, 0x80000
	s_mov_b64 s[18:19], 0x90000
	s_mov_b32 s50, 0x90000
	s_mov_b64 s[20:21], 0xa0000
	s_mov_b32 s51, 0xa0000
	s_mov_b64 s[22:23], 0xb0000
	s_mov_b32 s52, 0xb0000
	s_add_u32 s58, s26, 0x160080
	s_addc_u32 s59, s27, 0
	s_add_i32 m0, s37, 0xc000
	s_nop 0
	global_load_lds_dwordx4 v130, s[58:59]
	s_barrier
	s_branch .LBB0_937
